# every workgroup writes back its L2 lines before arriving at a grid barrier (shortens the last arriver's release)
# baseline (speedup 1.0000x reference)
; __device__ __forceinline__ void ssm_matrices(KArgsP a, int l, int g, LAS unsigned char* lds, bf16_t* Bm, bf16_t* Mt) {
;     ...
;     for (int idx = tid; idx < 32 * 256; idx += 512) { const int tau = idx >> 8, ho = (idx >> 4) & 15, hi = idx & 15; float s = 0.f;
;         for (int p = 0; p < NP; ++p) { const f32x2 c = cc[ho * 64 + p], lm = lamtab[tau * 64 + p], b = bb[p * 16 + hi];
;             const float wr_ = c[0] * lm[0] - c[1] * lm[1], wi_ = c[0] * lm[1] + c[1] * lm[0]; s += wr_ * b[0] - wi_ * b[1]; }
;         if (tau == 0 && ho == hi) s += dd[ho];
;         Kt[idx] = s; }
.LBB0_114:
	s_or_b64 exec, exec, s[48:49]
	s_waitcnt vmcnt(0)
	v_mul_f32_e32 v10, v124, v10
	ds_write_b32 v5, v10
	s_and_saveexec_b64 s[4:5], s[6:7]
	s_xor_b64 s[6:7], exec, s[4:5]
	s_cbranch_execz .LBB0_116
	buffer_wbl2 sc1
	s_waitcnt vmcnt(0)
	v_add_lshl_u32 v10, v21, v6, 2
	v_lshl_add_u64 v[126:127], v[18:19], 0, v[10:11]
	global_load_dword v10, v[126:127], off offset:8

; __device__ __forceinline__ unsigned xb_ld(unsigned* p)              { return __hip_atomic_load(p, __ATOMIC_RELAXED, __HIP_MEMORY_SCOPE_AGENT); }
; __device__ __forceinline__ unsigned xb_add(unsigned* p, unsigned v) { return __hip_atomic_fetch_add(p, v, __ATOMIC_RELAXED, __HIP_MEMORY_SCOPE_AGENT); }
; #define XB_SPIN(cond, bar) do { unsigned _sp = 0; while (cond) { __builtin_amdgcn_s_sleep(1); \
;     if ((++_sp & 255u) == 0u) { if (xb_ld(&(bar)[XB_TMO])) break; if (_sp > XB_SPIN_CAP) { atomicAdd(&(bar)[XB_TMO], 1u); break; } } } } while (0)
; #define GSYNC() do { XcdBarrier xb_; xb_.bar = (unsigned*)(KARGS()->ws + WS_CTL) + 1024; xb_.x = xb_xcc_id(); xb_.st = (volatile LAS unsigned*)(lds + LDS_XB); xcd_barrier(xb_); } while (0)
; __device__ __forceinline__ void xcd_barrier(const XcdBarrier& b) {
;     asm volatile("s_waitcnt vmcnt(0)" ::: "memory");
;     __syncthreads();
;     if (threadIdx.x == 0) {
;         unsigned* bar = b.bar;
;         __builtin_amdgcn_s_waitcnt(0);
;         unsigned nloc = b.st[0], nx = b.st[1];
;         if (nloc == 0u) { xcd_barrier_complete(bar, b.x, nloc, nx); b.st[0] = nloc; b.st[1] = nx; }
;         const unsigned old = xb_add(&bar[XB_XSUB(b.x)], 1u);
;         const unsigned gen = old / nloc;
;         if (old + 1u == (gen + 1u) * nloc) {
;             __builtin_amdgcn_fence(__ATOMIC_RELEASE, "agent");
;             asm volatile("s_waitcnt vmcnt(0)" ::: "memory");
;             const unsigned og = xb_add(&bar[XB_TOP], 1u);
;             const unsigned tg = og / nx;
;             if (og + 1u == (tg + 1u) * nx) xb_add(&bar[XB_TOPGEN], 1u);
;             else XB_SPIN(xb_ld(&bar[XB_TOPGEN]) == tg, bar);
;             __builtin_amdgcn_fence(__ATOMIC_ACQUIRE, "agent");
;             xb_add(&bar[XB_XGEN(b.x)], 1u);
;             asm volatile("s_waitcnt vmcnt(0)" ::: "memory");
;         } else {
;             XB_SPIN(xb_ld(&bar[XB_XGEN(b.x)]) == gen, bar);
;             __builtin_amdgcn_fence(__ATOMIC_ACQUIRE, "agent");
;             asm volatile("s_waitcnt vmcnt(0)" ::: "memory");
;         }
;     }
;     __syncthreads();
; }
; __global__ void __launch_bounds__(512, 2) fwd_kernel(Args a) {
;     ...
;         GSYNC();
.LBB0_535:
	s_mov_b64 s[8:9], s[0:1]
	s_getreg_b32 s2, hwreg(HW_REG_XCC_ID, 0, 4)
	s_waitcnt vmcnt(0)
	v_readlane_b32 s6, v255, 0
	v_readlane_b32 s7, v255, 1
	s_waitcnt vmcnt(0)
	s_barrier
	v_readlane_b32 s4, v255, 40
	s_nop 1
	s_cmp_eq_u32 s4, 0
	s_cbranch_scc1 .Lfs0
	s_and_saveexec_b64 s[4:5], s[6:7]
	s_cbranch_execz .Lfe0
	s_load_dwordx2 s[8:9], s[0:1], 0x128
	v_readlane_b32 s10, v255, 41
	v_readlane_b32 s11, v255, 8
	s_nop 1
	s_and_b32 s11, s11, 63
	s_lshl_b32 s11, s11, 6
	s_addk_i32 s11, 0x6200
	v_mov_b32_e32 v2, 0
	v_mov_b32_e32 v3, 1
	s_add_i32 s10, s10, 1
	s_lshl_b32 s10, s10, 2
	s_waitcnt lgkmcnt(0)
	s_add_u32 s8, s8, s11
	s_addc_u32 s9, s9, 0
	global_atomic_add v2, v3, s[8:9]

; __device__ __forceinline__ unsigned xb_ld(unsigned* p)              { return __hip_atomic_load(p, __ATOMIC_RELAXED, __HIP_MEMORY_SCOPE_AGENT); }
; __device__ __forceinline__ unsigned xb_add(unsigned* p, unsigned v) { return __hip_atomic_fetch_add(p, v, __ATOMIC_RELAXED, __HIP_MEMORY_SCOPE_AGENT); }
; #define XB_SPIN(cond, bar) do { unsigned _sp = 0; while (cond) { __builtin_amdgcn_s_sleep(1); \
;     if ((++_sp & 255u) == 0u) { if (xb_ld(&(bar)[XB_TMO])) break; if (_sp > XB_SPIN_CAP) { atomicAdd(&(bar)[XB_TMO], 1u); break; } } } } while (0)
; __device__ __forceinline__ void xcd_barrier(const XcdBarrier& b) {
;     asm volatile("s_waitcnt vmcnt(0)" ::: "memory");
;     __syncthreads();
;     if (threadIdx.x == 0) {
;         unsigned* bar = b.bar;
;         __builtin_amdgcn_s_waitcnt(0);
;         unsigned nloc = b.st[0], nx = b.st[1];
;         if (nloc == 0u) { xcd_barrier_complete(bar, b.x, nloc, nx); b.st[0] = nloc; b.st[1] = nx; }
;         const unsigned old = xb_add(&bar[XB_XSUB(b.x)], 1u);
;         const unsigned gen = old / nloc;
;         if (old + 1u == (gen + 1u) * nloc) {
;             __builtin_amdgcn_fence(__ATOMIC_RELEASE, "agent");
;             asm volatile("s_waitcnt vmcnt(0)" ::: "memory");
;             const unsigned og = xb_add(&bar[XB_TOP], 1u);
;             const unsigned tg = og / nx;
;             if (og + 1u == (tg + 1u) * nx) xb_add(&bar[XB_TOPGEN], 1u);
;             else XB_SPIN(xb_ld(&bar[XB_TOPGEN]) == tg, bar);
.Lfs0:
	s_and_saveexec_b64 s[4:5], s[6:7]
	s_xor_b64 s[6:7], exec, s[4:5]
	s_cbranch_execz .LBB0_588
	buffer_wbl2 sc1
	s_waitcnt vmcnt(0)
	v_readlane_b32 s4, v255, 5
	s_load_dwordx2 s[8:9], s[8:9], 0x128
	s_waitcnt vmcnt(0) expcnt(0) lgkmcnt(0)
	v_mov_b32_e32 v0, s4
	ds_read_b32 v3, v0
	v_readlane_b32 s4, v255, 7
	s_and_b32 s2, s2, 15
	s_waitcnt lgkmcnt(0)
	v_cmp_ne_u32_e32 vcc, 0, v3
	v_mov_b32_e32 v0, s4
	ds_read_b32 v0, v0
	s_cbranch_vccnz .LBB0_551
	s_add_u32 s10, s8, 0x1200
	s_addc_u32 s11, s9, 0
	s_add_u32 s12, s8, 0x1400
	s_addc_u32 s13, s9, 0
	s_add_u32 s14, s8, 0x1500
	s_addc_u32 s15, s9, 0
	s_add_u32 s16, s8, 0x1600
	s_addc_u32 s17, s9, 0
	s_add_u32 s46, s8, 0x1700
	s_addc_u32 s47, s9, 0
	s_add_u32 s52, s8, 0x1800
	s_addc_u32 s53, s9, 0
	s_add_u32 s54, s8, 0x1900
	s_addc_u32 s55, s9, 0
	s_add_u32 s56, s8, 0x1a00
	s_addc_u32 s57, s9, 0
	s_add_u32 s58, s8, 0x1b00
	s_addc_u32 s59, s9, 0
	s_add_u32 s60, s8, 0x1c00
	s_addc_u32 s61, s9, 0
	s_add_u32 s62, s8, 0x1d00
	s_addc_u32 s63, s9, 0
	s_add_u32 s64, s8, 0x1e00
	s_addc_u32 s65, s9, 0
	s_add_u32 s66, s8, 0x1f00
	s_addc_u32 s67, s9, 0
	s_add_u32 s68, s8, 0x2000
	s_addc_u32 s69, s9, 0
	s_add_u32 s70, s8, 0x2100
	s_addc_u32 s71, s9, 0
	s_add_u32 s72, s8, 0x2200
	s_addc_u32 s73, s9, 0
	s_add_u32 s74, s8, 0x2300
	s_addc_u32 s75, s9, 0
	s_mov_b32 s4, 1
	s_branch .LBB0_539

; __device__ __forceinline__ unsigned xb_ld(unsigned* p)              { return __hip_atomic_load(p, __ATOMIC_RELAXED, __HIP_MEMORY_SCOPE_AGENT); }
; __device__ __forceinline__ unsigned xb_add(unsigned* p, unsigned v) { return __hip_atomic_fetch_add(p, v, __ATOMIC_RELAXED, __HIP_MEMORY_SCOPE_AGENT); }
; #define XB_SPIN(cond, bar) do { unsigned _sp = 0; while (cond) { __builtin_amdgcn_s_sleep(1); \
;     if ((++_sp & 255u) == 0u) { if (xb_ld(&(bar)[XB_TMO])) break; if (_sp > XB_SPIN_CAP) { atomicAdd(&(bar)[XB_TMO], 1u); break; } } } } while (0)
; #define GSYNC() do { XcdBarrier xb_; xb_.bar = (unsigned*)(KARGS()->ws + WS_CTL) + 1024; xb_.x = xb_xcc_id(); xb_.st = (volatile LAS unsigned*)(lds + LDS_XB); xcd_barrier(xb_); } while (0)
; __device__ __forceinline__ void xcd_barrier(const XcdBarrier& b) {
;     asm volatile("s_waitcnt vmcnt(0)" ::: "memory");
;     __syncthreads();
;     if (threadIdx.x == 0) {
;         unsigned* bar = b.bar;
;         __builtin_amdgcn_s_waitcnt(0);
;         unsigned nloc = b.st[0], nx = b.st[1];
;         if (nloc == 0u) { xcd_barrier_complete(bar, b.x, nloc, nx); b.st[0] = nloc; b.st[1] = nx; }
;         const unsigned old = xb_add(&bar[XB_XSUB(b.x)], 1u);
;         const unsigned gen = old / nloc;
;         if (old + 1u == (gen + 1u) * nloc) {
;             __builtin_amdgcn_fence(__ATOMIC_RELEASE, "agent");
;             asm volatile("s_waitcnt vmcnt(0)" ::: "memory");
;             const unsigned og = xb_add(&bar[XB_TOP], 1u);
;             const unsigned tg = og / nx;
;             if (og + 1u == (tg + 1u) * nx) xb_add(&bar[XB_TOPGEN], 1u);
;             else XB_SPIN(xb_ld(&bar[XB_TOPGEN]) == tg, bar);
;             __builtin_amdgcn_fence(__ATOMIC_ACQUIRE, "agent");
;             xb_add(&bar[XB_XGEN(b.x)], 1u);
;             asm volatile("s_waitcnt vmcnt(0)" ::: "memory");
;         } else {
;             XB_SPIN(xb_ld(&bar[XB_XGEN(b.x)]) == gen, bar);
;             __builtin_amdgcn_fence(__ATOMIC_ACQUIRE, "agent");
;             asm volatile("s_waitcnt vmcnt(0)" ::: "memory");
;         }
;     }
;     __syncthreads();
; }
; __global__ void __launch_bounds__(512, 2) fwd_kernel(Args a) {
;     ...
;         GSYNC();
.LBB0_630:
	s_mov_b64 s[8:9], s[0:1]
	s_getreg_b32 s2, hwreg(HW_REG_XCC_ID, 0, 4)
	s_waitcnt vmcnt(0)
	s_waitcnt lgkmcnt(0)
	v_readlane_b32 s6, v255, 0
	v_readlane_b32 s7, v255, 1
	s_barrier
	v_readlane_b32 s4, v255, 40
	s_nop 1
	s_cmp_eq_u32 s4, 0
	s_branch .Lfs1
	s_and_saveexec_b64 s[4:5], s[6:7]
	s_cbranch_execz .Lfe1
	s_load_dwordx2 s[8:9], s[0:1], 0x128
	v_readlane_b32 s10, v255, 41
	v_readlane_b32 s11, v255, 8
	s_nop 1
	s_and_b32 s11, s11, 63
	s_lshl_b32 s11, s11, 6
	s_addk_i32 s11, 0x6200
	v_mov_b32_e32 v2, 0
	v_mov_b32_e32 v3, 1
	s_add_i32 s10, s10, 1
	s_lshl_b32 s10, s10, 2
	s_waitcnt lgkmcnt(0)
	s_add_u32 s8, s8, s11
	s_addc_u32 s9, s9, 0
	global_atomic_add v2, v3, s[8:9]

; __device__ __forceinline__ unsigned xb_ld(unsigned* p)              { return __hip_atomic_load(p, __ATOMIC_RELAXED, __HIP_MEMORY_SCOPE_AGENT); }
; __device__ __forceinline__ unsigned xb_add(unsigned* p, unsigned v) { return __hip_atomic_fetch_add(p, v, __ATOMIC_RELAXED, __HIP_MEMORY_SCOPE_AGENT); }
; #define XB_SPIN(cond, bar) do { unsigned _sp = 0; while (cond) { __builtin_amdgcn_s_sleep(1); \
;     if ((++_sp & 255u) == 0u) { if (xb_ld(&(bar)[XB_TMO])) break; if (_sp > XB_SPIN_CAP) { atomicAdd(&(bar)[XB_TMO], 1u); break; } } } } while (0)
; __device__ __forceinline__ void xcd_barrier(const XcdBarrier& b) {
;     asm volatile("s_waitcnt vmcnt(0)" ::: "memory");
;     __syncthreads();
;     if (threadIdx.x == 0) {
;         unsigned* bar = b.bar;
;         __builtin_amdgcn_s_waitcnt(0);
;         unsigned nloc = b.st[0], nx = b.st[1];
;         if (nloc == 0u) { xcd_barrier_complete(bar, b.x, nloc, nx); b.st[0] = nloc; b.st[1] = nx; }
;         const unsigned old = xb_add(&bar[XB_XSUB(b.x)], 1u);
;         const unsigned gen = old / nloc;
;         if (old + 1u == (gen + 1u) * nloc) {
;             __builtin_amdgcn_fence(__ATOMIC_RELEASE, "agent");
;             asm volatile("s_waitcnt vmcnt(0)" ::: "memory");
;             const unsigned og = xb_add(&bar[XB_TOP], 1u);
;             const unsigned tg = og / nx;
;             if (og + 1u == (tg + 1u) * nx) xb_add(&bar[XB_TOPGEN], 1u);
;             else XB_SPIN(xb_ld(&bar[XB_TOPGEN]) == tg, bar);
.Lfs1:
	s_and_saveexec_b64 s[4:5], s[6:7]
	s_xor_b64 s[6:7], exec, s[4:5]
	s_cbranch_execz .LBB0_683
	buffer_wbl2 sc1
	s_waitcnt vmcnt(0)
	v_readlane_b32 s4, v255, 5
	s_load_dwordx2 s[8:9], s[8:9], 0x128
	s_waitcnt vmcnt(0) expcnt(0) lgkmcnt(0)
	v_mov_b32_e32 v0, s4
	ds_read_b32 v3, v0
	v_readlane_b32 s4, v255, 7
	s_and_b32 s2, s2, 15
	s_waitcnt lgkmcnt(0)
	v_cmp_ne_u32_e32 vcc, 0, v3
	v_mov_b32_e32 v0, s4
	ds_read_b32 v2, v0
	s_cbranch_vccnz .LBB0_646
	s_add_u32 s10, s8, 0x1200
	s_addc_u32 s11, s9, 0
	s_add_u32 s12, s8, 0x1400
	s_addc_u32 s13, s9, 0
	s_add_u32 s14, s8, 0x1500
	s_addc_u32 s15, s9, 0
	s_add_u32 s16, s8, 0x1600
	s_addc_u32 s17, s9, 0
	s_add_u32 s52, s8, 0x1700
	s_addc_u32 s53, s9, 0
	s_add_u32 s54, s8, 0x1800
	s_addc_u32 s55, s9, 0
	s_add_u32 s56, s8, 0x1900
	s_addc_u32 s57, s9, 0
	s_add_u32 s58, s8, 0x1a00
	s_addc_u32 s59, s9, 0
	s_add_u32 s60, s8, 0x1b00
	s_addc_u32 s61, s9, 0
	s_add_u32 s62, s8, 0x1c00
	s_addc_u32 s63, s9, 0
	s_add_u32 s64, s8, 0x1d00
	s_addc_u32 s65, s9, 0
	s_add_u32 s66, s8, 0x1e00
	s_addc_u32 s67, s9, 0
	s_add_u32 s68, s8, 0x1f00
	s_addc_u32 s69, s9, 0
	s_add_u32 s70, s8, 0x2000
	s_addc_u32 s71, s9, 0
	s_add_u32 s72, s8, 0x2100
	s_addc_u32 s73, s9, 0
	s_add_u32 s74, s8, 0x2200
	s_addc_u32 s75, s9, 0
	s_add_u32 s76, s8, 0x2300
	s_addc_u32 s77, s9, 0
	s_mov_b32 s4, 1
	s_branch .LBB0_634

; __device__ __forceinline__ unsigned xb_ld(unsigned* p)              { return __hip_atomic_load(p, __ATOMIC_RELAXED, __HIP_MEMORY_SCOPE_AGENT); }
; __device__ __forceinline__ unsigned xb_add(unsigned* p, unsigned v) { return __hip_atomic_fetch_add(p, v, __ATOMIC_RELAXED, __HIP_MEMORY_SCOPE_AGENT); }
; #define XB_SPIN(cond, bar) do { unsigned _sp = 0; while (cond) { __builtin_amdgcn_s_sleep(1); \
;     if ((++_sp & 255u) == 0u) { if (xb_ld(&(bar)[XB_TMO])) break; if (_sp > XB_SPIN_CAP) { atomicAdd(&(bar)[XB_TMO], 1u); break; } } } } while (0)
; __device__ __forceinline__ void xcd_barrier(const XcdBarrier& b) {
;     asm volatile("s_waitcnt vmcnt(0)" ::: "memory");
;     __syncthreads();
;     if (threadIdx.x == 0) {
;         unsigned* bar = b.bar;
;         __builtin_amdgcn_s_waitcnt(0);
;         unsigned nloc = b.st[0], nx = b.st[1];
;         if (nloc == 0u) { xcd_barrier_complete(bar, b.x, nloc, nx); b.st[0] = nloc; b.st[1] = nx; }
;         const unsigned old = xb_add(&bar[XB_XSUB(b.x)], 1u);
;         const unsigned gen = old / nloc;
;         if (old + 1u == (gen + 1u) * nloc) {
;             __builtin_amdgcn_fence(__ATOMIC_RELEASE, "agent");
;             asm volatile("s_waitcnt vmcnt(0)" ::: "memory");
;             const unsigned og = xb_add(&bar[XB_TOP], 1u);
;             const unsigned tg = og / nx;
;             if (og + 1u == (tg + 1u) * nx) xb_add(&bar[XB_TOPGEN], 1u);
;             else XB_SPIN(xb_ld(&bar[XB_TOPGEN]) == tg, bar);
.LBB0_949:
	s_mov_b64 s[8:9], s[0:1]
	s_getreg_b32 s2, hwreg(HW_REG_XCC_ID, 0, 4)
	s_waitcnt vmcnt(0)
	v_readlane_b32 s6, v255, 0
	v_readlane_b32 s7, v255, 1
	s_waitcnt vmcnt(0) lgkmcnt(0)
	s_barrier
	s_and_saveexec_b64 s[4:5], s[6:7]
	s_load_dwordx2 s[94:95], s[0:1], 0x130
	s_xor_b64 s[6:7], exec, s[4:5]
	s_cbranch_execz .LBB0_1002
	buffer_wbl2 sc1
	s_waitcnt vmcnt(0)
	v_readlane_b32 s4, v255, 5
	s_load_dwordx2 s[8:9], s[8:9], 0x128
	s_waitcnt vmcnt(0) expcnt(0) lgkmcnt(0)
	v_mov_b32_e32 v0, s4
	ds_read_b32 v3, v0
	v_readlane_b32 s4, v255, 7
	s_and_b32 s2, s2, 15
	s_waitcnt lgkmcnt(0)
	v_cmp_ne_u32_e32 vcc, 0, v3
	v_mov_b32_e32 v0, s4
	ds_read_b32 v2, v0
	s_cbranch_vccnz .LBB0_965
	s_add_u32 s10, s8, 0x1200
	s_addc_u32 s11, s9, 0
	s_add_u32 s12, s8, 0x1400
	s_addc_u32 s13, s9, 0
	s_add_u32 s14, s8, 0x1500
	s_addc_u32 s15, s9, 0
	s_add_u32 s16, s8, 0x1600
	s_addc_u32 s17, s9, 0
	s_add_u32 s52, s8, 0x1700
	s_addc_u32 s53, s9, 0
	s_add_u32 s54, s8, 0x1800
	s_addc_u32 s55, s9, 0
	s_add_u32 s56, s8, 0x1900
	s_addc_u32 s57, s9, 0
	s_add_u32 s58, s8, 0x1a00
	s_addc_u32 s59, s9, 0
	s_add_u32 s60, s8, 0x1b00
	s_addc_u32 s61, s9, 0
	s_add_u32 s62, s8, 0x1c00
	s_addc_u32 s63, s9, 0
	s_add_u32 s64, s8, 0x1d00
	s_addc_u32 s65, s9, 0
	s_add_u32 s66, s8, 0x1e00
	s_addc_u32 s67, s9, 0
	s_add_u32 s68, s8, 0x1f00
	s_addc_u32 s69, s9, 0
	s_add_u32 s70, s8, 0x2000
	s_addc_u32 s71, s9, 0
	s_add_u32 s72, s8, 0x2100
	s_addc_u32 s73, s9, 0
	s_add_u32 s74, s8, 0x2200
	s_addc_u32 s75, s9, 0
	s_add_u32 s76, s8, 0x2300
	s_addc_u32 s77, s9, 0
	s_mov_b32 s4, 1
	s_branch .LBB0_953

; __device__ __forceinline__ unsigned xb_ld(unsigned* p)              { return __hip_atomic_load(p, __ATOMIC_RELAXED, __HIP_MEMORY_SCOPE_AGENT); }
; __device__ __forceinline__ unsigned xb_add(unsigned* p, unsigned v) { return __hip_atomic_fetch_add(p, v, __ATOMIC_RELAXED, __HIP_MEMORY_SCOPE_AGENT); }
; #define XB_SPIN(cond, bar) do { unsigned _sp = 0; while (cond) { __builtin_amdgcn_s_sleep(1); \
;     if ((++_sp & 255u) == 0u) { if (xb_ld(&(bar)[XB_TMO])) break; if (_sp > XB_SPIN_CAP) { atomicAdd(&(bar)[XB_TMO], 1u); break; } } } } while (0)
; __device__ __forceinline__ void xcd_barrier(const XcdBarrier& b) {
;     asm volatile("s_waitcnt vmcnt(0)" ::: "memory");
;     __syncthreads();
;     if (threadIdx.x == 0) {
;         unsigned* bar = b.bar;
;         __builtin_amdgcn_s_waitcnt(0);
;         unsigned nloc = b.st[0], nx = b.st[1];
;         if (nloc == 0u) { xcd_barrier_complete(bar, b.x, nloc, nx); b.st[0] = nloc; b.st[1] = nx; }
;         const unsigned old = xb_add(&bar[XB_XSUB(b.x)], 1u);
;         const unsigned gen = old / nloc;
;         if (old + 1u == (gen + 1u) * nloc) {
;             __builtin_amdgcn_fence(__ATOMIC_RELEASE, "agent");
;             asm volatile("s_waitcnt vmcnt(0)" ::: "memory");
;             const unsigned og = xb_add(&bar[XB_TOP], 1u);
;             const unsigned tg = og / nx;
;             if (og + 1u == (tg + 1u) * nx) xb_add(&bar[XB_TOPGEN], 1u);
;             else XB_SPIN(xb_ld(&bar[XB_TOPGEN]) == tg, bar);
.LBB0_1115:
	s_mov_b64 s[8:9], s[0:1]
	s_getreg_b32 s2, hwreg(HW_REG_XCC_ID, 0, 4)
	s_waitcnt vmcnt(0)
	v_readlane_b32 s6, v255, 0
	v_readlane_b32 s7, v255, 1
	s_waitcnt vmcnt(0)
	s_barrier
	s_and_saveexec_b64 s[4:5], s[6:7]
	s_xor_b64 s[6:7], exec, s[4:5]
	s_cbranch_execz .LBB0_1168
	buffer_wbl2 sc1
	s_waitcnt vmcnt(0)
	v_readlane_b32 s4, v255, 5
	s_load_dwordx2 s[8:9], s[8:9], 0x128
	s_waitcnt vmcnt(0) expcnt(0) lgkmcnt(0)
	v_mov_b32_e32 v0, s4
	ds_read_b32 v3, v0
	v_readlane_b32 s4, v255, 7
	s_and_b32 s2, s2, 15
	s_waitcnt lgkmcnt(0)
	v_cmp_ne_u32_e32 vcc, 0, v3
	v_mov_b32_e32 v0, s4
	ds_read_b32 v2, v0
	s_cbranch_vccnz .LBB0_1131
	s_add_u32 s10, s8, 0x1200
	s_addc_u32 s11, s9, 0
	s_add_u32 s12, s8, 0x1400
	s_addc_u32 s13, s9, 0
	s_add_u32 s14, s8, 0x1500
	s_addc_u32 s15, s9, 0
	s_add_u32 s16, s8, 0x1600
	s_addc_u32 s17, s9, 0
	s_add_u32 s50, s8, 0x1700
	s_addc_u32 s51, s9, 0
	s_add_u32 s52, s8, 0x1800
	s_addc_u32 s53, s9, 0
	s_add_u32 s54, s8, 0x1900
	s_addc_u32 s55, s9, 0
	s_add_u32 s56, s8, 0x1a00
	s_addc_u32 s57, s9, 0
	s_add_u32 s58, s8, 0x1b00
	s_addc_u32 s59, s9, 0
	s_add_u32 s60, s8, 0x1c00
	s_addc_u32 s61, s9, 0
	s_add_u32 s62, s8, 0x1d00
	s_addc_u32 s63, s9, 0
	s_add_u32 s64, s8, 0x1e00
	s_addc_u32 s65, s9, 0
	s_add_u32 s66, s8, 0x1f00
	s_addc_u32 s67, s9, 0
	s_add_u32 s68, s8, 0x2000
	s_addc_u32 s69, s9, 0
	s_add_u32 s70, s8, 0x2100
	s_addc_u32 s71, s9, 0
	s_add_u32 s72, s8, 0x2200
	s_addc_u32 s73, s9, 0
	s_add_u32 s74, s8, 0x2300
	s_addc_u32 s75, s9, 0
	s_mov_b32 s4, 1
	s_branch .LBB0_1119

; __device__ __forceinline__ unsigned xb_ld(unsigned* p)              { return __hip_atomic_load(p, __ATOMIC_RELAXED, __HIP_MEMORY_SCOPE_AGENT); }
; __device__ __forceinline__ unsigned xb_add(unsigned* p, unsigned v) { return __hip_atomic_fetch_add(p, v, __ATOMIC_RELAXED, __HIP_MEMORY_SCOPE_AGENT); }
; #define XB_SPIN(cond, bar) do { unsigned _sp = 0; while (cond) { __builtin_amdgcn_s_sleep(1); \
;     if ((++_sp & 255u) == 0u) { if (xb_ld(&(bar)[XB_TMO])) break; if (_sp > XB_SPIN_CAP) { atomicAdd(&(bar)[XB_TMO], 1u); break; } } } } while (0)
; __device__ __forceinline__ void xcd_barrier(const XcdBarrier& b) {
;     asm volatile("s_waitcnt vmcnt(0)" ::: "memory");
;     __syncthreads();
;     if (threadIdx.x == 0) {
;         unsigned* bar = b.bar;
;         __builtin_amdgcn_s_waitcnt(0);
;         unsigned nloc = b.st[0], nx = b.st[1];
;         if (nloc == 0u) { xcd_barrier_complete(bar, b.x, nloc, nx); b.st[0] = nloc; b.st[1] = nx; }
;         const unsigned old = xb_add(&bar[XB_XSUB(b.x)], 1u);
;         const unsigned gen = old / nloc;
;         if (old + 1u == (gen + 1u) * nloc) {
;             __builtin_amdgcn_fence(__ATOMIC_RELEASE, "agent");
;             asm volatile("s_waitcnt vmcnt(0)" ::: "memory");
;             const unsigned og = xb_add(&bar[XB_TOP], 1u);
;             const unsigned tg = og / nx;
;             if (og + 1u == (tg + 1u) * nx) xb_add(&bar[XB_TOPGEN], 1u);
;             else XB_SPIN(xb_ld(&bar[XB_TOPGEN]) == tg, bar);
.LBB0_1277:
	s_mov_b64 s[8:9], s[0:1]
	s_getreg_b32 s2, hwreg(HW_REG_XCC_ID, 0, 4)
	s_waitcnt vmcnt(0)
	s_waitcnt lgkmcnt(0)
	v_readlane_b32 s6, v255, 0
	v_readlane_b32 s7, v255, 1
	s_barrier
	s_and_saveexec_b64 s[4:5], s[6:7]
	s_xor_b64 s[6:7], exec, s[4:5]
	s_cbranch_execz .LBB0_1330
	buffer_wbl2 sc1
	s_waitcnt vmcnt(0)
	v_readlane_b32 s4, v255, 5
	s_load_dwordx2 s[8:9], s[8:9], 0x128
	s_waitcnt vmcnt(0) expcnt(0) lgkmcnt(0)
	v_mov_b32_e32 v0, s4
	ds_read_b32 v3, v0
	v_readlane_b32 s4, v255, 7
	s_and_b32 s2, s2, 15
	s_waitcnt lgkmcnt(0)
	v_cmp_ne_u32_e32 vcc, 0, v3
	v_mov_b32_e32 v0, s4
	ds_read_b32 v2, v0
	s_cbranch_vccnz .LBB0_1293
	s_add_u32 s10, s8, 0x1200
	s_addc_u32 s11, s9, 0
	s_add_u32 s12, s8, 0x1400
	s_addc_u32 s13, s9, 0
	s_add_u32 s14, s8, 0x1500
	s_addc_u32 s15, s9, 0
	s_add_u32 s16, s8, 0x1600
	s_addc_u32 s17, s9, 0
	s_add_u32 s52, s8, 0x1700
	s_addc_u32 s53, s9, 0
	s_add_u32 s54, s8, 0x1800
	s_addc_u32 s55, s9, 0
	s_add_u32 s56, s8, 0x1900
	s_addc_u32 s57, s9, 0
	s_add_u32 s58, s8, 0x1a00
	s_addc_u32 s59, s9, 0
	s_add_u32 s60, s8, 0x1b00
	s_addc_u32 s61, s9, 0
	s_add_u32 s62, s8, 0x1c00
	s_addc_u32 s63, s9, 0
	s_add_u32 s64, s8, 0x1d00
	s_addc_u32 s65, s9, 0
	s_add_u32 s66, s8, 0x1e00
	s_addc_u32 s67, s9, 0
	s_add_u32 s68, s8, 0x1f00
	s_addc_u32 s69, s9, 0
	s_add_u32 s70, s8, 0x2000
	s_addc_u32 s71, s9, 0
	s_add_u32 s72, s8, 0x2100
	s_addc_u32 s73, s9, 0
	s_add_u32 s74, s8, 0x2200
	s_addc_u32 s75, s9, 0
	s_add_u32 s76, s8, 0x2300
	s_addc_u32 s77, s9, 0
	s_mov_b32 s4, 1
	s_branch .LBB0_1281

; __device__ __forceinline__ unsigned xb_ld(unsigned* p)              { return __hip_atomic_load(p, __ATOMIC_RELAXED, __HIP_MEMORY_SCOPE_AGENT); }
; __device__ __forceinline__ unsigned xb_add(unsigned* p, unsigned v) { return __hip_atomic_fetch_add(p, v, __ATOMIC_RELAXED, __HIP_MEMORY_SCOPE_AGENT); }
; #define XB_SPIN(cond, bar) do { unsigned _sp = 0; while (cond) { __builtin_amdgcn_s_sleep(1); \
;     if ((++_sp & 255u) == 0u) { if (xb_ld(&(bar)[XB_TMO])) break; if (_sp > XB_SPIN_CAP) { atomicAdd(&(bar)[XB_TMO], 1u); break; } } } } while (0)
; #define GSYNC() do { XcdBarrier xb_; xb_.bar = (unsigned*)(KARGS()->ws + WS_CTL) + 1024; xb_.x = xb_xcc_id(); xb_.st = (volatile LAS unsigned*)(lds + LDS_XB); xcd_barrier(xb_); } while (0)
; __device__ __forceinline__ void xcd_barrier(const XcdBarrier& b) {
;     asm volatile("s_waitcnt vmcnt(0)" ::: "memory");
;     __syncthreads();
;     if (threadIdx.x == 0) {
;         unsigned* bar = b.bar;
;         __builtin_amdgcn_s_waitcnt(0);
;         unsigned nloc = b.st[0], nx = b.st[1];
;         if (nloc == 0u) { xcd_barrier_complete(bar, b.x, nloc, nx); b.st[0] = nloc; b.st[1] = nx; }
;         const unsigned old = xb_add(&bar[XB_XSUB(b.x)], 1u);
;         const unsigned gen = old / nloc;
;         if (old + 1u == (gen + 1u) * nloc) {
;             __builtin_amdgcn_fence(__ATOMIC_RELEASE, "agent");
;             asm volatile("s_waitcnt vmcnt(0)" ::: "memory");
;             const unsigned og = xb_add(&bar[XB_TOP], 1u);
;             const unsigned tg = og / nx;
;             if (og + 1u == (tg + 1u) * nx) xb_add(&bar[XB_TOPGEN], 1u);
;             else XB_SPIN(xb_ld(&bar[XB_TOPGEN]) == tg, bar);
;             __builtin_amdgcn_fence(__ATOMIC_ACQUIRE, "agent");
;             xb_add(&bar[XB_XGEN(b.x)], 1u);
;             asm volatile("s_waitcnt vmcnt(0)" ::: "memory");
;         } else {
;             XB_SPIN(xb_ld(&bar[XB_XGEN(b.x)]) == gen, bar);
;             __builtin_amdgcn_fence(__ATOMIC_ACQUIRE, "agent");
;             asm volatile("s_waitcnt vmcnt(0)" ::: "memory");
;         }
;     }
;     __syncthreads();
; }
; __global__ void __launch_bounds__(512, 2) fwd_kernel(Args a) {
;     ...
;         GSYNC();
.LBB0_1525:
	s_mov_b64 s[8:9], s[0:1]
	s_getreg_b32 s2, hwreg(HW_REG_XCC_ID, 0, 4)
	s_waitcnt vmcnt(0)
	v_readlane_b32 s6, v255, 0
	v_readlane_b32 s7, v255, 1
	s_waitcnt lgkmcnt(0)
	s_barrier
	v_readlane_b32 s4, v255, 40
	s_nop 1
	s_cmp_eq_u32 s4, 0
	s_branch .Lfs2
	s_and_saveexec_b64 s[4:5], s[6:7]
	s_cbranch_execz .Lfe2
	s_load_dwordx2 s[8:9], s[0:1], 0x128
	v_readlane_b32 s10, v255, 41
	v_readlane_b32 s11, v255, 8
	s_nop 1
	s_and_b32 s11, s11, 63
	s_lshl_b32 s11, s11, 6
	s_addk_i32 s11, 0x6200
	v_mov_b32_e32 v2, 0
	v_mov_b32_e32 v3, 1
	s_add_i32 s10, s10, 1
	s_lshl_b32 s10, s10, 2
	s_waitcnt lgkmcnt(0)
	s_add_u32 s8, s8, s11
	s_addc_u32 s9, s9, 0
	global_atomic_add v2, v3, s[8:9]

; __device__ __forceinline__ unsigned xb_ld(unsigned* p)              { return __hip_atomic_load(p, __ATOMIC_RELAXED, __HIP_MEMORY_SCOPE_AGENT); }
; __device__ __forceinline__ unsigned xb_add(unsigned* p, unsigned v) { return __hip_atomic_fetch_add(p, v, __ATOMIC_RELAXED, __HIP_MEMORY_SCOPE_AGENT); }
; #define XB_SPIN(cond, bar) do { unsigned _sp = 0; while (cond) { __builtin_amdgcn_s_sleep(1); \
;     if ((++_sp & 255u) == 0u) { if (xb_ld(&(bar)[XB_TMO])) break; if (_sp > XB_SPIN_CAP) { atomicAdd(&(bar)[XB_TMO], 1u); break; } } } } while (0)
; __device__ __forceinline__ void xcd_barrier(const XcdBarrier& b) {
;     asm volatile("s_waitcnt vmcnt(0)" ::: "memory");
;     __syncthreads();
;     if (threadIdx.x == 0) {
;         unsigned* bar = b.bar;
;         __builtin_amdgcn_s_waitcnt(0);
;         unsigned nloc = b.st[0], nx = b.st[1];
;         if (nloc == 0u) { xcd_barrier_complete(bar, b.x, nloc, nx); b.st[0] = nloc; b.st[1] = nx; }
;         const unsigned old = xb_add(&bar[XB_XSUB(b.x)], 1u);
;         const unsigned gen = old / nloc;
;         if (old + 1u == (gen + 1u) * nloc) {
;             __builtin_amdgcn_fence(__ATOMIC_RELEASE, "agent");
;             asm volatile("s_waitcnt vmcnt(0)" ::: "memory");
;             const unsigned og = xb_add(&bar[XB_TOP], 1u);
;             const unsigned tg = og / nx;
;             if (og + 1u == (tg + 1u) * nx) xb_add(&bar[XB_TOPGEN], 1u);
;             else XB_SPIN(xb_ld(&bar[XB_TOPGEN]) == tg, bar);
.Lfs2:
	s_and_saveexec_b64 s[4:5], s[6:7]
	s_xor_b64 s[6:7], exec, s[4:5]
	s_cbranch_execz .LBB0_1578
	buffer_wbl2 sc1
	s_waitcnt vmcnt(0)
	v_readlane_b32 s4, v255, 5
	s_load_dwordx2 s[8:9], s[8:9], 0x128
	s_waitcnt vmcnt(0) expcnt(0) lgkmcnt(0)
	v_mov_b32_e32 v0, s4
	ds_read_b32 v3, v0
	v_readlane_b32 s4, v255, 7
	s_and_b32 s2, s2, 15
	s_waitcnt lgkmcnt(0)
	v_cmp_ne_u32_e32 vcc, 0, v3
	v_mov_b32_e32 v0, s4
	ds_read_b32 v2, v0
	s_cbranch_vccnz .LBB0_1541
	s_add_u32 s10, s8, 0x1200
	s_addc_u32 s11, s9, 0
	s_add_u32 s12, s8, 0x1400
	s_addc_u32 s13, s9, 0
	s_add_u32 s14, s8, 0x1500
	s_addc_u32 s15, s9, 0
	s_add_u32 s16, s8, 0x1600
	s_addc_u32 s17, s9, 0
	s_add_u32 s48, s8, 0x1700
	s_addc_u32 s49, s9, 0
	s_add_u32 s52, s8, 0x1800
	s_addc_u32 s53, s9, 0
	s_add_u32 s54, s8, 0x1900
	s_addc_u32 s55, s9, 0
	s_add_u32 s56, s8, 0x1a00
	s_addc_u32 s57, s9, 0
	s_add_u32 s58, s8, 0x1b00
	s_addc_u32 s59, s9, 0
	s_add_u32 s60, s8, 0x1c00
	s_addc_u32 s61, s9, 0
	s_add_u32 s62, s8, 0x1d00
	s_addc_u32 s63, s9, 0
	s_add_u32 s64, s8, 0x1e00
	s_addc_u32 s65, s9, 0
	s_add_u32 s66, s8, 0x1f00
	s_addc_u32 s67, s9, 0
	s_add_u32 s68, s8, 0x2000
	s_addc_u32 s69, s9, 0
	s_add_u32 s70, s8, 0x2100
	s_addc_u32 s71, s9, 0
	s_add_u32 s72, s8, 0x2200
	s_addc_u32 s73, s9, 0
	s_add_u32 s74, s8, 0x2300
	s_addc_u32 s75, s9, 0
	s_mov_b32 s4, 1
	s_branch .LBB0_1529

; __device__ __forceinline__ unsigned xb_ld(unsigned* p)              { return __hip_atomic_load(p, __ATOMIC_RELAXED, __HIP_MEMORY_SCOPE_AGENT); }
; __device__ __forceinline__ unsigned xb_add(unsigned* p, unsigned v) { return __hip_atomic_fetch_add(p, v, __ATOMIC_RELAXED, __HIP_MEMORY_SCOPE_AGENT); }
; #define XB_SPIN(cond, bar) do { unsigned _sp = 0; while (cond) { __builtin_amdgcn_s_sleep(1); \
;     if ((++_sp & 255u) == 0u) { if (xb_ld(&(bar)[XB_TMO])) break; if (_sp > XB_SPIN_CAP) { atomicAdd(&(bar)[XB_TMO], 1u); break; } } } } while (0)
; __device__ __forceinline__ void xcd_barrier(const XcdBarrier& b) {
;     asm volatile("s_waitcnt vmcnt(0)" ::: "memory");
;     __syncthreads();
;     if (threadIdx.x == 0) {
;         unsigned* bar = b.bar;
;         __builtin_amdgcn_s_waitcnt(0);
;         unsigned nloc = b.st[0], nx = b.st[1];
;         if (nloc == 0u) { xcd_barrier_complete(bar, b.x, nloc, nx); b.st[0] = nloc; b.st[1] = nx; }
;         const unsigned old = xb_add(&bar[XB_XSUB(b.x)], 1u);
;         const unsigned gen = old / nloc;
;         if (old + 1u == (gen + 1u) * nloc) {
;             __builtin_amdgcn_fence(__ATOMIC_RELEASE, "agent");
;             asm volatile("s_waitcnt vmcnt(0)" ::: "memory");
;             const unsigned og = xb_add(&bar[XB_TOP], 1u);
;             const unsigned tg = og / nx;
;             if (og + 1u == (tg + 1u) * nx) xb_add(&bar[XB_TOPGEN], 1u);
;             else XB_SPIN(xb_ld(&bar[XB_TOPGEN]) == tg, bar);
.Lfs3:
	s_and_saveexec_b64 s[4:5], s[6:7]
	s_xor_b64 s[6:7], exec, s[4:5]
	s_cbranch_execz .LBB0_1873
	buffer_wbl2 sc1
	s_waitcnt vmcnt(0)
	v_readlane_b32 s4, v255, 5
	s_load_dwordx2 s[8:9], s[8:9], 0x128
	s_waitcnt vmcnt(0) expcnt(0) lgkmcnt(0)
	v_mov_b32_e32 v0, s4
	ds_read_b32 v3, v0
	v_readlane_b32 s4, v255, 7
	s_and_b32 s2, s2, 15
	s_waitcnt lgkmcnt(0)
	v_cmp_ne_u32_e32 vcc, 0, v3
	v_mov_b32_e32 v0, s4
	ds_read_b32 v0, v0
	s_cbranch_vccnz .LBB0_1836
	s_add_u32 s10, s8, 0x1200
	s_addc_u32 s11, s9, 0
	s_add_u32 s12, s8, 0x1400
	s_addc_u32 s13, s9, 0
	s_add_u32 s14, s8, 0x1500
	s_addc_u32 s15, s9, 0
	s_add_u32 s16, s8, 0x1600
	s_addc_u32 s17, s9, 0
	s_add_u32 s48, s8, 0x1700
	s_addc_u32 s49, s9, 0
	s_add_u32 s50, s8, 0x1800
	s_addc_u32 s51, s9, 0
	s_add_u32 s52, s8, 0x1900
	s_addc_u32 s53, s9, 0
	s_add_u32 s54, s8, 0x1a00
	s_addc_u32 s55, s9, 0
	s_add_u32 s56, s8, 0x1b00
	s_addc_u32 s57, s9, 0
	s_add_u32 s58, s8, 0x1c00
	s_addc_u32 s59, s9, 0
	s_add_u32 s60, s8, 0x1d00
	s_addc_u32 s61, s9, 0
	s_add_u32 s62, s8, 0x1e00
	s_addc_u32 s63, s9, 0
	s_add_u32 s64, s8, 0x1f00
	s_addc_u32 s65, s9, 0
	s_add_u32 s66, s8, 0x2000
	s_addc_u32 s67, s9, 0
	s_add_u32 s68, s8, 0x2100
	s_addc_u32 s69, s9, 0
	s_add_u32 s70, s8, 0x2200
	s_addc_u32 s71, s9, 0
	s_add_u32 s72, s8, 0x2300
	s_addc_u32 s73, s9, 0
	s_mov_b32 s4, 1
	s_branch .LBB0_1824

; __device__ __forceinline__ unsigned xb_ld(unsigned* p)              { return __hip_atomic_load(p, __ATOMIC_RELAXED, __HIP_MEMORY_SCOPE_AGENT); }
; __device__ __forceinline__ unsigned xb_add(unsigned* p, unsigned v) { return __hip_atomic_fetch_add(p, v, __ATOMIC_RELAXED, __HIP_MEMORY_SCOPE_AGENT); }
; #define XB_SPIN(cond, bar) do { unsigned _sp = 0; while (cond) { __builtin_amdgcn_s_sleep(1); \
;     if ((++_sp & 255u) == 0u) { if (xb_ld(&(bar)[XB_TMO])) break; if (_sp > XB_SPIN_CAP) { atomicAdd(&(bar)[XB_TMO], 1u); break; } } } } while (0)
; #define GSYNC() do { XcdBarrier xb_; xb_.bar = (unsigned*)(KARGS()->ws + WS_CTL) + 1024; xb_.x = xb_xcc_id(); xb_.st = (volatile LAS unsigned*)(lds + LDS_XB); xcd_barrier(xb_); } while (0)
; __device__ __forceinline__ void xcd_barrier(const XcdBarrier& b) {
;     asm volatile("s_waitcnt vmcnt(0)" ::: "memory");
;     __syncthreads();
;     if (threadIdx.x == 0) {
;         unsigned* bar = b.bar;
;         __builtin_amdgcn_s_waitcnt(0);
;         unsigned nloc = b.st[0], nx = b.st[1];
;         if (nloc == 0u) { xcd_barrier_complete(bar, b.x, nloc, nx); b.st[0] = nloc; b.st[1] = nx; }
;         const unsigned old = xb_add(&bar[XB_XSUB(b.x)], 1u);
;         const unsigned gen = old / nloc;
;         if (old + 1u == (gen + 1u) * nloc) {
;             __builtin_amdgcn_fence(__ATOMIC_RELEASE, "agent");
;             asm volatile("s_waitcnt vmcnt(0)" ::: "memory");
;             const unsigned og = xb_add(&bar[XB_TOP], 1u);
;             const unsigned tg = og / nx;
;             if (og + 1u == (tg + 1u) * nx) xb_add(&bar[XB_TOPGEN], 1u);
;             else XB_SPIN(xb_ld(&bar[XB_TOPGEN]) == tg, bar);
;             __builtin_amdgcn_fence(__ATOMIC_ACQUIRE, "agent");
;             xb_add(&bar[XB_XGEN(b.x)], 1u);
;             asm volatile("s_waitcnt vmcnt(0)" ::: "memory");
;         } else {
;             XB_SPIN(xb_ld(&bar[XB_XGEN(b.x)]) == gen, bar);
;             __builtin_amdgcn_fence(__ATOMIC_ACQUIRE, "agent");
;             asm volatile("s_waitcnt vmcnt(0)" ::: "memory");
;         }
;     }
;     __syncthreads();
; }
; __global__ void __launch_bounds__(512, 2) fwd_kernel(Args a) {
;     ...
;         GSYNC();
.LBB0_2010:
	s_mov_b64 s[8:9], s[0:1]
	s_getreg_b32 s2, hwreg(HW_REG_XCC_ID, 0, 4)
	s_waitcnt vmcnt(0)
	v_readlane_b32 s6, v255, 0
	v_readlane_b32 s7, v255, 1
	s_waitcnt vmcnt(0) lgkmcnt(0)
	s_barrier
	v_readlane_b32 s4, v255, 40
	s_nop 1
	s_cmp_eq_u32 s4, 0
	s_cbranch_scc1 .Lfs5
	s_and_saveexec_b64 s[4:5], s[6:7]
	s_cbranch_execz .Lfe5
	s_load_dwordx2 s[8:9], s[0:1], 0x128
	v_readlane_b32 s10, v255, 41
	v_readlane_b32 s11, v255, 8
	s_nop 1
	s_and_b32 s11, s11, 63
	s_lshl_b32 s11, s11, 6
	s_addk_i32 s11, 0x6200
	v_mov_b32_e32 v2, 0
	v_mov_b32_e32 v3, 1
	s_add_i32 s10, s10, 1
	s_lshl_b32 s10, s10, 2
	s_waitcnt lgkmcnt(0)
	s_add_u32 s8, s8, s11
	s_addc_u32 s9, s9, 0
	global_atomic_add v2, v3, s[8:9]
